# ctx_resid_gemm: all 8 B fragments per iteration loaded up front (16 loads in flight, counted waits)
# baseline (speedup 1.0000x reference)
; #define MFMA16(a, b, c) __builtin_amdgcn_mfma_f32_16x16x32_bf16((a), (b), (c), 0, 0, 0)
; __device__ __forceinline__ void ctx_resid_gemm(const bf16_t* A  , const bf16_t* Bt  , int K, float* XC, const float* gate  , float coef, int gw, int NGW, int lane) {
;     const int fr = lane & 15, fq = lane >> 4;
;     for (int tile = gw; tile < 32 * 64; tile += NGW) {
;         const int rt = tile >> 6, ct = tile & 63;
;         const bf16_t* ap = A + (size_t)(MX + rt * 16 + fr) * K + 8 * fq; const bf16_t* bp = Bt + (size_t)(ct * 16 + fr) * K + 8 * fq;
;         f32x4 acc0 = {0.f, 0.f, 0.f, 0.f}, acc1 = acc0;
; #pragma unroll 4
;         for (int ks = 0; ks < K; ks += 64) {
;             acc0 = MFMA16(*(const bf16x8*)(ap + ks), *(const bf16x8*)(bp + ks), acc0);
;             acc1 = MFMA16(*(const bf16x8*)(ap + ks + 32), *(const bf16x8*)(bp + ks + 32), acc1);
;         }
;         const int col = ct * 16 + fr; const float gv = gate[col] * coef;
; #pragma unroll
;         for (int e = 0; e < 4; ++e) { float* xp = XC + (size_t)(rt * 16 + 4 * fq + e) * D + col; *xp = *xp + gv * (acc0[e] + acc1[e]); }
;     }
; }
.LBB0_322:
	v_lshl_add_u64 v[22:23], v[16:17], 0, v[8:9]
	v_add_co_u32_e32 v62, vcc, 0xa600000, v22
	v_lshl_add_u64 v[24:25], v[14:15], 0, v[8:9]
	s_nop 0
	v_addc_co_u32_e32 v63, vcc, 0, v23, vcc
	v_add_co_u32_e32 v64, vcc, 0xc00000, v24
	s_addk_i32 s12, 0x100
	s_nop 0
	v_addc_co_u32_e32 v65, vcc, 0, v25, vcc
	global_load_dwordx4 v[22:25], v[62:63], off
	global_load_dwordx4 v[26:29], v[62:63], off offset:64
	global_load_dwordx4 v[30:33], v[62:63], off offset:128
	global_load_dwordx4 v[34:37], v[62:63], off offset:192
	global_load_dwordx4 v[38:41], v[62:63], off offset:256
	global_load_dwordx4 v[42:45], v[62:63], off offset:320
	global_load_dwordx4 v[46:49], v[62:63], off offset:384
	global_load_dwordx4 v[50:53], v[62:63], off offset:448
	global_load_dwordx4 v[54:57], v[64:65], off
	global_load_dwordx4 v[58:61], v[64:65], off offset:64
	global_load_dwordx4 v[66:69], v[64:65], off offset:128
	global_load_dwordx4 v[70:73], v[64:65], off offset:192
	global_load_dwordx4 v[74:77], v[64:65], off offset:256
	global_load_dwordx4 v[78:81], v[64:65], off offset:320
	global_load_dwordx4 v[82:85], v[64:65], off offset:384
	global_load_dwordx4 v[86:89], v[64:65], off offset:448
	v_lshl_add_u64 v[14:15], v[14:15], 0, s[8:9]
	s_cmpk_gt_u32 s12, 0xabf
	v_lshl_add_u64 v[16:17], v[16:17], 0, s[8:9]
	s_waitcnt vmcnt(7)
	v_mfma_f32_16x16x32_bf16 v[0:3], v[22:25], v[54:57], v[0:3]
	s_waitcnt vmcnt(6)
	v_mfma_f32_16x16x32_bf16 v[4:7], v[26:29], v[58:61], v[4:7]
	s_waitcnt vmcnt(5)
	v_mfma_f32_16x16x32_bf16 v[0:3], v[30:33], v[66:69], v[0:3]
	s_waitcnt vmcnt(4)
	v_mfma_f32_16x16x32_bf16 v[4:7], v[34:37], v[70:73], v[4:7]
	s_waitcnt vmcnt(3)
	v_mfma_f32_16x16x32_bf16 v[0:3], v[38:41], v[74:77], v[0:3]
	s_waitcnt vmcnt(2)
	v_mfma_f32_16x16x32_bf16 v[4:7], v[42:45], v[78:81], v[4:7]
	s_waitcnt vmcnt(1)
	v_mfma_f32_16x16x32_bf16 v[0:3], v[46:49], v[82:85], v[0:3]
	s_waitcnt vmcnt(0)
	v_mfma_f32_16x16x32_bf16 v[4:7], v[50:53], v[86:89], v[4:7]
	s_cbranch_scc0 .LBB0_322
	v_or_b32_e32 v14, s11, v20
	v_ashrrev_i32_e32 v15, 31, v14
	v_or_b32_e32 v24, 1, v14
	v_lshlrev_b32_e32 v10, 2, v10
	v_lshlrev_b64 v[22:23], 12, v[14:15]
	v_ashrrev_i32_e32 v25, 31, v24
	v_or_b32_e32 v26, 2, v14
	v_or_b32_e32 v14, 3, v14
	v_lshl_add_u64 v[16:17], s[4:5], 0, v[10:11]
	v_lshlrev_b64 v[24:25], 12, v[24:25]
	v_ashrrev_i32_e32 v27, 31, v26
	v_ashrrev_i32_e32 v15, 31, v14
	v_lshl_add_u64 v[22:23], v[16:17], 0, v[22:23]
	global_load_dword v21, v10, s[6:7]
	global_load_dword v28, v[22:23], off
	v_lshl_add_u64 v[24:25], v[16:17], 0, v[24:25]
	v_lshlrev_b64 v[26:27], 12, v[26:27]
	v_lshlrev_b64 v[14:15], 12, v[14:15]
	v_lshl_add_u64 v[26:27], v[16:17], 0, v[26:27]
	v_lshl_add_u64 v[14:15], v[16:17], 0, v[14:15]
	global_load_dword v10, v[24:25], off
	global_load_dword v16, v[26:27], off
	global_load_dword v17, v[14:15], off
	v_add_f32_e32 v0, v0, v4
	v_add_f32_e32 v1, v1, v5
	s_add_i32 s3, s3, s28
	v_add_f32_e32 v2, v2, v6
	v_add_f32_e32 v3, v3, v7
	s_cmpk_gt_i32 s3, 0x7ff
	s_waitcnt vmcnt(4)
	v_mul_f32_e32 v4, 0.5, v21
	s_waitcnt vmcnt(3)
	v_fmac_f32_e32 v28, v0, v4
	global_store_dword v[22:23], v28, off
	s_waitcnt vmcnt(3)
	v_fmac_f32_e32 v10, v1, v4
	s_waitcnt vmcnt(2)
	v_fmac_f32_e32 v16, v2, v4
	s_waitcnt vmcnt(1)
	v_fmac_f32_e32 v17, v3, v4
	global_store_dword v[24:25], v10, off
	global_store_dword v[26:27], v16, off
	global_store_dword v[14:15], v17, off
	s_cbranch_scc0 .LBB0_321

; #define MFMA16(a, b, c) __builtin_amdgcn_mfma_f32_16x16x32_bf16((a), (b), (c), 0, 0, 0)
; __device__ __forceinline__ void ctx_resid_gemm(const bf16_t* A  , const bf16_t* Bt  , int K, float* XC, const float* gate  , float coef, int gw, int NGW, int lane) {
;     const int fr = lane & 15, fq = lane >> 4;
;     for (int tile = gw; tile < 32 * 64; tile += NGW) {
;         const int rt = tile >> 6, ct = tile & 63;
;         const bf16_t* ap = A + (size_t)(MX + rt * 16 + fr) * K + 8 * fq; const bf16_t* bp = Bt + (size_t)(ct * 16 + fr) * K + 8 * fq;
;         f32x4 acc0 = {0.f, 0.f, 0.f, 0.f}, acc1 = acc0;
; #pragma unroll 4
;         for (int ks = 0; ks < K; ks += 64) {
;             acc0 = MFMA16(*(const bf16x8*)(ap + ks), *(const bf16x8*)(bp + ks), acc0);
;             acc1 = MFMA16(*(const bf16x8*)(ap + ks + 32), *(const bf16x8*)(bp + ks + 32), acc1);
;         }
;         const int col = ct * 16 + fr; const float gv = gate[col] * coef;
; #pragma unroll
;         for (int e = 0; e < 4; ++e) { float* xp = XC + (size_t)(rt * 16 + 4 * fq + e) * D + col; *xp = *xp + gv * (acc0[e] + acc1[e]); }
;     }
; }
.LBB0_1133:
	v_lshl_add_u64 v[20:21], v[14:15], 0, v[8:9]
	v_add_co_u32_e32 v60, vcc, 0xe700000, v20
	v_lshl_add_u64 v[22:23], v[12:13], 0, v[8:9]
	s_nop 0
	v_addc_co_u32_e32 v61, vcc, 0, v21, vcc
	v_add_co_u32_e32 v62, vcc, 0x1e80000, v22
	s_addk_i32 s20, 0x100
	s_nop 0
	v_addc_co_u32_e32 v63, vcc, 0, v23, vcc
	global_load_dwordx4 v[20:23], v[60:61], off
	global_load_dwordx4 v[24:27], v[60:61], off offset:64
	global_load_dwordx4 v[28:31], v[60:61], off offset:128
	global_load_dwordx4 v[32:35], v[60:61], off offset:192
	global_load_dwordx4 v[36:39], v[60:61], off offset:256
	global_load_dwordx4 v[40:43], v[60:61], off offset:320
	global_load_dwordx4 v[44:47], v[60:61], off offset:384
	global_load_dwordx4 v[48:51], v[60:61], off offset:448
	global_load_dwordx4 v[52:55], v[62:63], off
	global_load_dwordx4 v[56:59], v[62:63], off offset:64
	global_load_dwordx4 v[66:69], v[62:63], off offset:128
	global_load_dwordx4 v[70:73], v[62:63], off offset:192
	global_load_dwordx4 v[74:77], v[62:63], off offset:256
	global_load_dwordx4 v[78:81], v[62:63], off offset:320
	global_load_dwordx4 v[82:85], v[62:63], off offset:384
	global_load_dwordx4 v[86:89], v[62:63], off offset:448
	v_lshl_add_u64 v[12:13], v[12:13], 0, s[18:19]
	s_cmpk_gt_u32 s20, 0x3bf
	v_lshl_add_u64 v[14:15], v[14:15], 0, s[18:19]
	s_waitcnt vmcnt(7)
	v_mfma_f32_16x16x32_bf16 v[0:3], v[20:23], v[52:55], v[0:3]
	s_waitcnt vmcnt(6)
	v_mfma_f32_16x16x32_bf16 v[4:7], v[24:27], v[56:59], v[4:7]
	s_waitcnt vmcnt(5)
	v_mfma_f32_16x16x32_bf16 v[0:3], v[28:31], v[66:69], v[0:3]
	s_waitcnt vmcnt(4)
	v_mfma_f32_16x16x32_bf16 v[4:7], v[32:35], v[70:73], v[4:7]
	s_waitcnt vmcnt(3)
	v_mfma_f32_16x16x32_bf16 v[0:3], v[36:39], v[74:77], v[0:3]
	s_waitcnt vmcnt(2)
	v_mfma_f32_16x16x32_bf16 v[4:7], v[40:43], v[78:81], v[4:7]
	s_waitcnt vmcnt(1)
	v_mfma_f32_16x16x32_bf16 v[0:3], v[44:47], v[82:85], v[0:3]
	s_waitcnt vmcnt(0)
	v_mfma_f32_16x16x32_bf16 v[4:7], v[48:51], v[86:89], v[4:7]
	s_cbranch_scc0 .LBB0_1133
	s_lshl_b32 s16, s6, 4
	v_or_b32_e32 v12, s9, v18
	s_and_b32 s16, s16, 0x3f0
	v_ashrrev_i32_e32 v13, 31, v12
	v_or_b32_e32 v10, s16, v16
	v_lshlrev_b64 v[20:21], 12, v[12:13]
	v_or_b32_e32 v22, 1, v12
	v_or_b32_e32 v24, 2, v12
	v_or_b32_e32 v12, 3, v12
	v_lshlrev_b32_e32 v10, 2, v10
	v_ashrrev_i32_e32 v23, 31, v22
	v_ashrrev_i32_e32 v25, 31, v24
	v_ashrrev_i32_e32 v13, 31, v12
	v_lshl_add_u64 v[14:15], s[12:13], 0, v[10:11]
	v_lshlrev_b64 v[22:23], 12, v[22:23]
	v_lshlrev_b64 v[24:25], 12, v[24:25]
	v_lshlrev_b64 v[12:13], 12, v[12:13]
	v_lshl_add_u64 v[20:21], v[14:15], 0, v[20:21]
	v_lshl_add_u64 v[22:23], v[14:15], 0, v[22:23]
	v_lshl_add_u64 v[24:25], v[14:15], 0, v[24:25]
	v_lshl_add_u64 v[12:13], v[14:15], 0, v[12:13]
	global_load_dword v14, v10, s[14:15]
	global_load_dword v15, v[20:21], off
	global_load_dword v19, v[22:23], off
	global_load_dword v26, v[24:25], off
	global_load_dword v27, v[12:13], off
	v_add_f32_e32 v0, v0, v4
	s_add_i32 s6, s6, s28
	s_add_i32 s7, s7, s8
	v_add_f32_e32 v1, v1, v5
	v_add_f32_e32 v2, v2, v6
	v_add_f32_e32 v3, v3, v7
	s_cmpk_gt_i32 s6, 0x7ff
	s_waitcnt vmcnt(3)
	v_fmac_f32_e32 v15, v0, v14
	s_waitcnt vmcnt(2)
	v_fmac_f32_e32 v19, v1, v14
	s_waitcnt vmcnt(1)
	v_fmac_f32_e32 v26, v2, v14
	s_waitcnt vmcnt(0)
	v_fmac_f32_e32 v27, v3, v14
	global_store_dword v[20:21], v15, off
	global_store_dword v[22:23], v19, off
	global_store_dword v[24:25], v26, off
	global_store_dword v[12:13], v27, off
	s_cbranch_scc0 .LBB0_1132

; #define MFMA16(a, b, c) __builtin_amdgcn_mfma_f32_16x16x32_bf16((a), (b), (c), 0, 0, 0)
; __device__ __forceinline__ void ctx_resid_gemm(const bf16_t* A  , const bf16_t* Bt  , int K, float* XC, const float* gate  , float coef, int gw, int NGW, int lane) {
;     const int fr = lane & 15, fq = lane >> 4;
;     for (int tile = gw; tile < 32 * 64; tile += NGW) {
;         const int rt = tile >> 6, ct = tile & 63;
;         const bf16_t* ap = A + (size_t)(MX + rt * 16 + fr) * K + 8 * fq; const bf16_t* bp = Bt + (size_t)(ct * 16 + fr) * K + 8 * fq;
;         f32x4 acc0 = {0.f, 0.f, 0.f, 0.f}, acc1 = acc0;
; #pragma unroll 4
;         for (int ks = 0; ks < K; ks += 64) {
;             acc0 = MFMA16(*(const bf16x8*)(ap + ks), *(const bf16x8*)(bp + ks), acc0);
;             acc1 = MFMA16(*(const bf16x8*)(ap + ks + 32), *(const bf16x8*)(bp + ks + 32), acc1);
;         }
;         const int col = ct * 16 + fr; const float gv = gate[col] * coef;
; #pragma unroll
;         for (int e = 0; e < 4; ++e) { float* xp = XC + (size_t)(rt * 16 + 4 * fq + e) * D + col; *xp = *xp + gv * (acc0[e] + acc1[e]); }
;     }
; }
.LBB0_1353:
	v_lshl_add_u64 v[22:23], v[16:17], 0, v[8:9]
	v_add_co_u32_e32 v62, vcc, 0xa600000, v22
	v_lshl_add_u64 v[24:25], v[14:15], 0, v[8:9]
	s_nop 0
	v_addc_co_u32_e32 v63, vcc, 0, v23, vcc
	v_add_co_u32_e32 v64, vcc, 0x2b80000, v24
	s_addk_i32 s9, 0x100
	s_nop 0
	v_addc_co_u32_e32 v65, vcc, 0, v25, vcc
	global_load_dwordx4 v[22:25], v[62:63], off
	global_load_dwordx4 v[26:29], v[62:63], off offset:64
	global_load_dwordx4 v[30:33], v[62:63], off offset:128
	global_load_dwordx4 v[34:37], v[62:63], off offset:192
	global_load_dwordx4 v[38:41], v[62:63], off offset:256
	global_load_dwordx4 v[42:45], v[62:63], off offset:320
	global_load_dwordx4 v[46:49], v[62:63], off offset:384
	global_load_dwordx4 v[50:53], v[62:63], off offset:448
	global_load_dwordx4 v[54:57], v[64:65], off
	global_load_dwordx4 v[58:61], v[64:65], off offset:64
	global_load_dwordx4 v[66:69], v[64:65], off offset:128
	global_load_dwordx4 v[70:73], v[64:65], off offset:192
	global_load_dwordx4 v[74:77], v[64:65], off offset:256
	global_load_dwordx4 v[78:81], v[64:65], off offset:320
	global_load_dwordx4 v[82:85], v[64:65], off offset:384
	global_load_dwordx4 v[86:89], v[64:65], off offset:448
	v_lshl_add_u64 v[14:15], v[14:15], 0, s[16:17]
	s_cmpk_gt_u32 s9, 0xabf
	v_lshl_add_u64 v[16:17], v[16:17], 0, s[16:17]
	s_waitcnt vmcnt(7)
	v_mfma_f32_16x16x32_bf16 v[0:3], v[22:25], v[54:57], v[0:3]
	s_waitcnt vmcnt(6)
	v_mfma_f32_16x16x32_bf16 v[4:7], v[26:29], v[58:61], v[4:7]
	s_waitcnt vmcnt(5)
	v_mfma_f32_16x16x32_bf16 v[0:3], v[30:33], v[66:69], v[0:3]
	s_waitcnt vmcnt(4)
	v_mfma_f32_16x16x32_bf16 v[4:7], v[34:37], v[70:73], v[4:7]
	s_waitcnt vmcnt(3)
	v_mfma_f32_16x16x32_bf16 v[0:3], v[38:41], v[74:77], v[0:3]
	s_waitcnt vmcnt(2)
	v_mfma_f32_16x16x32_bf16 v[4:7], v[42:45], v[78:81], v[4:7]
	s_waitcnt vmcnt(1)
	v_mfma_f32_16x16x32_bf16 v[0:3], v[46:49], v[82:85], v[0:3]
	s_waitcnt vmcnt(0)
	v_mfma_f32_16x16x32_bf16 v[4:7], v[50:53], v[86:89], v[4:7]
	s_cbranch_scc0 .LBB0_1353
	v_or_b32_e32 v14, s8, v20
	v_ashrrev_i32_e32 v15, 31, v14
	v_or_b32_e32 v24, 1, v14
	v_lshlrev_b32_e32 v10, 2, v10
	v_lshlrev_b64 v[22:23], 12, v[14:15]
	v_ashrrev_i32_e32 v25, 31, v24
	v_or_b32_e32 v26, 2, v14
	v_or_b32_e32 v14, 3, v14
	v_lshl_add_u64 v[16:17], s[12:13], 0, v[10:11]
	v_lshlrev_b64 v[24:25], 12, v[24:25]
	v_ashrrev_i32_e32 v27, 31, v26
	v_ashrrev_i32_e32 v15, 31, v14
	v_lshl_add_u64 v[22:23], v[16:17], 0, v[22:23]
	global_load_dword v21, v10, s[14:15]
	global_load_dword v28, v[22:23], off
	v_lshl_add_u64 v[24:25], v[16:17], 0, v[24:25]
	v_lshlrev_b64 v[26:27], 12, v[26:27]
	v_lshlrev_b64 v[14:15], 12, v[14:15]
	v_lshl_add_u64 v[26:27], v[16:17], 0, v[26:27]
	v_lshl_add_u64 v[14:15], v[16:17], 0, v[14:15]
	global_load_dword v10, v[24:25], off
	global_load_dword v16, v[26:27], off
	global_load_dword v17, v[14:15], off
	v_add_f32_e32 v0, v0, v4
	v_add_f32_e32 v1, v1, v5
	s_add_i32 s6, s6, s28
	v_add_f32_e32 v2, v2, v6
	v_add_f32_e32 v3, v3, v7
	s_cmpk_gt_i32 s6, 0x7ff
	s_waitcnt vmcnt(4)
	v_mul_f32_e32 v4, 0.5, v21
	s_waitcnt vmcnt(3)
	v_fmac_f32_e32 v28, v0, v4
	global_store_dword v[22:23], v28, off
	s_waitcnt vmcnt(3)
	v_fmac_f32_e32 v10, v1, v4
	s_waitcnt vmcnt(2)
	v_fmac_f32_e32 v16, v2, v4
	s_waitcnt vmcnt(1)
	v_fmac_f32_e32 v17, v3, v4
	global_store_dword v[24:25], v10, off
	global_store_dword v[26:27], v16, off
	global_store_dword v[14:15], v17, off
	s_cbranch_scc0 .LBB0_1352

; #define MFMA16(a, b, c) __builtin_amdgcn_mfma_f32_16x16x32_bf16((a), (b), (c), 0, 0, 0)
; __device__ __forceinline__ void ctx_resid_gemm(const bf16_t* A  , const bf16_t* Bt  , int K, float* XC, const float* gate  , float coef, int gw, int NGW, int lane) {
;     const int fr = lane & 15, fq = lane >> 4;
;     for (int tile = gw; tile < 32 * 64; tile += NGW) {
;         const int rt = tile >> 6, ct = tile & 63;
;         const bf16_t* ap = A + (size_t)(MX + rt * 16 + fr) * K + 8 * fq; const bf16_t* bp = Bt + (size_t)(ct * 16 + fr) * K + 8 * fq;
;         f32x4 acc0 = {0.f, 0.f, 0.f, 0.f}, acc1 = acc0;
; #pragma unroll 4
;         for (int ks = 0; ks < K; ks += 64) {
;             acc0 = MFMA16(*(const bf16x8*)(ap + ks), *(const bf16x8*)(bp + ks), acc0);
;             acc1 = MFMA16(*(const bf16x8*)(ap + ks + 32), *(const bf16x8*)(bp + ks + 32), acc1);
;         }
;         const int col = ct * 16 + fr; const float gv = gate[col] * coef;
; #pragma unroll
;         for (int e = 0; e < 4; ++e) { float* xp = XC + (size_t)(rt * 16 + 4 * fq + e) * D + col; *xp = *xp + gv * (acc0[e] + acc1[e]); }
;     }
; }
.LBB0_1573:
	v_lshl_add_u64 v[22:23], v[16:17], 0, v[8:9]
	v_add_co_u32_e32 v62, vcc, 0xa600000, v22
	v_lshl_add_u64 v[24:25], v[14:15], 0, v[8:9]
	s_nop 0
	v_addc_co_u32_e32 v63, vcc, 0, v23, vcc
	v_add_co_u32_e32 v64, vcc, 0x3d00000, v24
	s_addk_i32 s9, 0x100
	s_nop 0
	v_addc_co_u32_e32 v65, vcc, 0, v25, vcc
	global_load_dwordx4 v[22:25], v[62:63], off
	global_load_dwordx4 v[26:29], v[62:63], off offset:64
	global_load_dwordx4 v[30:33], v[62:63], off offset:128
	global_load_dwordx4 v[34:37], v[62:63], off offset:192
	global_load_dwordx4 v[38:41], v[62:63], off offset:256
	global_load_dwordx4 v[42:45], v[62:63], off offset:320
	global_load_dwordx4 v[46:49], v[62:63], off offset:384
	global_load_dwordx4 v[50:53], v[62:63], off offset:448
	global_load_dwordx4 v[54:57], v[64:65], off
	global_load_dwordx4 v[58:61], v[64:65], off offset:64
	global_load_dwordx4 v[66:69], v[64:65], off offset:128
	global_load_dwordx4 v[70:73], v[64:65], off offset:192
	global_load_dwordx4 v[74:77], v[64:65], off offset:256
	global_load_dwordx4 v[78:81], v[64:65], off offset:320
	global_load_dwordx4 v[82:85], v[64:65], off offset:384
	global_load_dwordx4 v[86:89], v[64:65], off offset:448
	v_lshl_add_u64 v[14:15], v[14:15], 0, s[14:15]
	s_cmpk_gt_u32 s9, 0xabf
	v_lshl_add_u64 v[16:17], v[16:17], 0, s[14:15]
	s_waitcnt vmcnt(7)
	v_mfma_f32_16x16x32_bf16 v[0:3], v[22:25], v[54:57], v[0:3]
	s_waitcnt vmcnt(6)
	v_mfma_f32_16x16x32_bf16 v[4:7], v[26:29], v[58:61], v[4:7]
	s_waitcnt vmcnt(5)
	v_mfma_f32_16x16x32_bf16 v[0:3], v[30:33], v[66:69], v[0:3]
	s_waitcnt vmcnt(4)
	v_mfma_f32_16x16x32_bf16 v[4:7], v[34:37], v[70:73], v[4:7]
	s_waitcnt vmcnt(3)
	v_mfma_f32_16x16x32_bf16 v[0:3], v[38:41], v[74:77], v[0:3]
	s_waitcnt vmcnt(2)
	v_mfma_f32_16x16x32_bf16 v[4:7], v[42:45], v[78:81], v[4:7]
	s_waitcnt vmcnt(1)
	v_mfma_f32_16x16x32_bf16 v[0:3], v[46:49], v[82:85], v[0:3]
	s_waitcnt vmcnt(0)
	v_mfma_f32_16x16x32_bf16 v[4:7], v[50:53], v[86:89], v[4:7]
	s_cbranch_scc0 .LBB0_1573
	v_or_b32_e32 v14, s8, v20
	v_ashrrev_i32_e32 v15, 31, v14
	v_or_b32_e32 v24, 1, v14
	v_lshlrev_b32_e32 v10, 2, v10
	v_lshlrev_b64 v[22:23], 12, v[14:15]
	v_ashrrev_i32_e32 v25, 31, v24
	v_or_b32_e32 v26, 2, v14
	v_or_b32_e32 v14, 3, v14
	v_lshl_add_u64 v[16:17], s[10:11], 0, v[10:11]
	v_lshlrev_b64 v[24:25], 12, v[24:25]
	v_ashrrev_i32_e32 v27, 31, v26
	v_ashrrev_i32_e32 v15, 31, v14
	v_lshl_add_u64 v[22:23], v[16:17], 0, v[22:23]
	global_load_dword v21, v10, s[12:13]
	global_load_dword v28, v[22:23], off
	v_lshl_add_u64 v[24:25], v[16:17], 0, v[24:25]
	v_lshlrev_b64 v[26:27], 12, v[26:27]
	v_lshlrev_b64 v[14:15], 12, v[14:15]
	v_lshl_add_u64 v[26:27], v[16:17], 0, v[26:27]
	v_lshl_add_u64 v[14:15], v[16:17], 0, v[14:15]
	global_load_dword v10, v[24:25], off
	global_load_dword v16, v[26:27], off
	global_load_dword v17, v[14:15], off
	v_add_f32_e32 v0, v0, v4
	v_add_f32_e32 v1, v1, v5
	s_add_i32 s6, s6, s28
	v_add_f32_e32 v2, v2, v6
	v_add_f32_e32 v3, v3, v7
	s_cmpk_gt_i32 s6, 0x7ff
	s_waitcnt vmcnt(4)
	v_mul_f32_e32 v4, 0.5, v21
	s_waitcnt vmcnt(3)
	v_fmac_f32_e32 v28, v0, v4
	global_store_dword v[22:23], v28, off
	s_waitcnt vmcnt(3)
	v_fmac_f32_e32 v10, v1, v4
	s_waitcnt vmcnt(2)
	v_fmac_f32_e32 v16, v2, v4
	s_waitcnt vmcnt(1)
	v_fmac_f32_e32 v17, v3, v4
	global_store_dword v[24:25], v10, off
	global_store_dword v[26:27], v16, off
	global_store_dword v[14:15], v17, off
	s_cbranch_scc0 .LBB0_1572
